# v13 + first 4 MFMAs of every 32-MFMA super-phase issued before the pre-MFMA s_barrier (fills the matrix-pipe hand-off bubble between the two wave groups)
# speedup vs baseline: 1.0233x; 1.0233x over previous
.LBB0_32:
	s_add_u32 s28, s54, 0xfff80080
	s_addc_u32 s29, s55, -1
	s_add_i32 s30, 0, 0x10000
	s_cmp_eq_u32 s27, 28
	s_cselect_b32 s79, s13, s29
	s_cselect_b32 s78, s16, s28
	s_cselect_b32 s69, s9, s26
	s_cselect_b32 s68, s24, s25
	s_add_i32 s31, 0, 0x14000
	v_add_u32_e32 v142, s30, v184
	v_add_u32_e32 v172, s31, v184
	ds_read_b128 v[130:133], v142
	ds_read_b128 v[134:137], v142 offset:1024
	ds_read_b128 v[138:141], v142 offset:2048
	ds_read_b128 v[142:145], v142 offset:3072
	ds_read_b128 v[146:149], v172
	ds_read_b128 v[150:153], v172 offset:1024
	ds_read_b128 v[154:157], v172 offset:2048
	ds_read_b128 v[172:175], v172 offset:3072
	v_lshl_add_u64 v[212:213], s[54:55], 0, v[166:167]
	s_add_i32 m0, s42, 0xc000
	ds_read_b128 v[176:179], v186
	ds_read_b128 v[180:183], v186 offset:1024
	ds_read_b128 v[188:191], v186 offset:2048
	ds_read_b128 v[192:195], v186 offset:3072
	ds_read_b128 v[196:199], v186 offset:4096
	ds_read_b128 v[200:203], v186 offset:5120
	ds_read_b128 v[204:207], v186 offset:6144
	ds_read_b128 v[208:211], v186 offset:7168
	global_load_lds_dwordx4 v[212:213], off
	v_lshl_add_u64 v[212:213], s[54:55], 0, v[168:169]
	s_add_i32 m0, s42, 0xe000
	s_nop 0
	global_load_lds_dwordx4 v[212:213], off
	s_waitcnt vmcnt(8)
	s_waitcnt lgkmcnt(0)
	v_mfma_f32_16x16x32_bf16 v[126:129], v[130:133], v[176:179], v[126:129]
	v_mfma_f32_16x16x32_bf16 v[126:129], v[134:137], v[180:183], v[126:129]
	v_mfma_f32_16x16x32_bf16 v[110:113], v[134:137], v[192:195], v[110:113]
	v_mfma_f32_16x16x32_bf16 v[110:113], v[130:133], v[188:191], v[110:113]
	s_barrier
	s_setprio 1
	s_waitcnt lgkmcnt(0)
	v_mfma_f32_16x16x32_bf16 v[94:97], v[130:133], v[196:199], v[94:97]
	v_mfma_f32_16x16x32_bf16 v[94:97], v[134:137], v[200:203], v[94:97]
	v_mfma_f32_16x16x32_bf16 v[78:81], v[134:137], v[208:211], v[78:81]
	v_mfma_f32_16x16x32_bf16 v[78:81], v[130:133], v[204:207], v[78:81]
	v_mfma_f32_16x16x32_bf16 v[74:77], v[138:141], v[204:207], v[74:77]
	v_mfma_f32_16x16x32_bf16 v[74:77], v[142:145], v[208:211], v[74:77]
	v_mfma_f32_16x16x32_bf16 v[90:93], v[142:145], v[200:203], v[90:93]
	v_mfma_f32_16x16x32_bf16 v[90:93], v[138:141], v[196:199], v[90:93]
	v_mfma_f32_16x16x32_bf16 v[106:109], v[138:141], v[188:191], v[106:109]
	v_mfma_f32_16x16x32_bf16 v[106:109], v[142:145], v[192:195], v[106:109]
	v_mfma_f32_16x16x32_bf16 v[122:125], v[142:145], v[180:183], v[122:125]
	v_mfma_f32_16x16x32_bf16 v[122:125], v[138:141], v[176:179], v[122:125]
	s_setprio 0
	s_setprio 1
	v_mfma_f32_16x16x32_bf16 v[118:121], v[146:149], v[176:179], v[118:121]
	v_mfma_f32_16x16x32_bf16 v[118:121], v[150:153], v[180:183], v[118:121]
	v_mfma_f32_16x16x32_bf16 v[102:105], v[150:153], v[192:195], v[102:105]
	v_mfma_f32_16x16x32_bf16 v[102:105], v[146:149], v[188:191], v[102:105]
	v_mfma_f32_16x16x32_bf16 v[86:89], v[146:149], v[196:199], v[86:89]
	v_mfma_f32_16x16x32_bf16 v[86:89], v[150:153], v[200:203], v[86:89]
	v_mfma_f32_16x16x32_bf16 v[70:73], v[150:153], v[208:211], v[70:73]
	v_mfma_f32_16x16x32_bf16 v[70:73], v[146:149], v[204:207], v[70:73]
	v_mfma_f32_16x16x32_bf16 v[66:69], v[154:157], v[204:207], v[66:69]
	v_mfma_f32_16x16x32_bf16 v[66:69], v[172:175], v[208:211], v[66:69]
	v_mfma_f32_16x16x32_bf16 v[82:85], v[172:175], v[200:203], v[82:85]
	v_mfma_f32_16x16x32_bf16 v[82:85], v[154:157], v[196:199], v[82:85]
	v_mfma_f32_16x16x32_bf16 v[98:101], v[154:157], v[188:191], v[98:101]
	v_mfma_f32_16x16x32_bf16 v[98:101], v[172:175], v[192:195], v[98:101]
	v_mfma_f32_16x16x32_bf16 v[114:117], v[172:175], v[180:183], v[114:117]
	v_mfma_f32_16x16x32_bf16 v[114:117], v[154:157], v[176:179], v[114:117]
	s_setprio 0
	s_barrier
	s_add_i32 s28, s30, s11
	v_lshl_add_u64 v[212:213], s[68:69], 0, v[160:161]
	s_mov_b32 m0, s28
	ds_read_b128 v[176:179], v186 offset:16384
	ds_read_b128 v[180:183], v186 offset:17408
	ds_read_b128 v[188:191], v186 offset:18432
	ds_read_b128 v[192:195], v186 offset:19456
	ds_read_b128 v[196:199], v186 offset:20480
	ds_read_b128 v[200:203], v186 offset:21504
	ds_read_b128 v[204:207], v186 offset:22528
	ds_read_b128 v[208:211], v186 offset:23552
	global_load_lds_dwordx4 v[212:213], off
	s_add_i32 m0, s28, 0x2000
	s_add_u32 s28, s68, 0x80000
	v_lshl_add_u64 v[232:233], s[68:69], 0, v[164:165]
	s_addc_u32 s29, s69, 0
	s_add_i32 s30, s31, s11
	global_load_lds_dwordx4 v[232:233], off
	v_lshl_add_u64 v[234:235], s[28:29], 0, v[160:161]
	s_mov_b32 m0, s30
	v_lshl_add_u64 v[236:237], s[78:79], 0, v[162:163]
	global_load_lds_dwordx4 v[234:235], off
	v_lshl_add_u64 v[234:235], s[28:29], 0, v[164:165]
	s_add_i32 m0, s30, 0x2000
	s_nop 0
	global_load_lds_dwordx4 v[234:235], off
	v_lshl_add_u64 v[234:235], s[78:79], 0, v[158:159]
	s_mov_b32 m0, s42
	s_nop 0
	global_load_lds_dwordx4 v[234:235], off
	s_mov_b32 m0, s57
	s_nop 0
	global_load_lds_dwordx4 v[236:237], off
	s_waitcnt vmcnt(8)
	s_waitcnt lgkmcnt(0)
	v_mfma_f32_16x16x32_bf16 v[62:65], v[130:133], v[176:179], v[62:65]
	v_mfma_f32_16x16x32_bf16 v[62:65], v[134:137], v[180:183], v[62:65]
	v_mfma_f32_16x16x32_bf16 v[46:49], v[134:137], v[192:195], v[46:49]
	v_mfma_f32_16x16x32_bf16 v[46:49], v[130:133], v[188:191], v[46:49]
	s_barrier
	s_setprio 1
	s_waitcnt lgkmcnt(0)
	v_mfma_f32_16x16x32_bf16 v[30:33], v[130:133], v[196:199], v[30:33]
	v_mfma_f32_16x16x32_bf16 v[30:33], v[134:137], v[200:203], v[30:33]
	v_mfma_f32_16x16x32_bf16 v[14:17], v[134:137], v[208:211], v[14:17]
	v_mfma_f32_16x16x32_bf16 v[14:17], v[130:133], v[204:207], v[14:17]
	v_mfma_f32_16x16x32_bf16 v[10:13], v[138:141], v[204:207], v[10:13]
	v_mfma_f32_16x16x32_bf16 v[10:13], v[142:145], v[208:211], v[10:13]
	v_mfma_f32_16x16x32_bf16 v[26:29], v[142:145], v[200:203], v[26:29]
	v_mfma_f32_16x16x32_bf16 v[26:29], v[138:141], v[196:199], v[26:29]
	v_mfma_f32_16x16x32_bf16 v[42:45], v[138:141], v[188:191], v[42:45]
	v_mfma_f32_16x16x32_bf16 v[42:45], v[142:145], v[192:195], v[42:45]
	v_mfma_f32_16x16x32_bf16 v[58:61], v[142:145], v[180:183], v[58:61]
	v_mfma_f32_16x16x32_bf16 v[58:61], v[138:141], v[176:179], v[58:61]
	s_setprio 0
	s_setprio 1
	v_mfma_f32_16x16x32_bf16 v[54:57], v[146:149], v[176:179], v[54:57]
	v_mfma_f32_16x16x32_bf16 v[54:57], v[150:153], v[180:183], v[54:57]
	v_mfma_f32_16x16x32_bf16 v[38:41], v[150:153], v[192:195], v[38:41]
	v_mfma_f32_16x16x32_bf16 v[38:41], v[146:149], v[188:191], v[38:41]
	v_mfma_f32_16x16x32_bf16 v[22:25], v[146:149], v[196:199], v[22:25]
	v_mfma_f32_16x16x32_bf16 v[22:25], v[150:153], v[200:203], v[22:25]
	v_mfma_f32_16x16x32_bf16 v[6:9], v[150:153], v[208:211], v[6:9]
	v_mfma_f32_16x16x32_bf16 v[6:9], v[146:149], v[204:207], v[6:9]
	v_mfma_f32_16x16x32_bf16 v[2:5], v[154:157], v[204:207], v[2:5]
	v_mfma_f32_16x16x32_bf16 v[2:5], v[172:175], v[208:211], v[2:5]
	v_mfma_f32_16x16x32_bf16 v[18:21], v[172:175], v[200:203], v[18:21]
	v_mfma_f32_16x16x32_bf16 v[18:21], v[154:157], v[196:199], v[18:21]
	v_mfma_f32_16x16x32_bf16 v[34:37], v[154:157], v[188:191], v[34:37]
	v_mfma_f32_16x16x32_bf16 v[34:37], v[172:175], v[192:195], v[34:37]
	v_mfma_f32_16x16x32_bf16 v[50:53], v[172:175], v[180:183], v[50:53]
	v_mfma_f32_16x16x32_bf16 v[50:53], v[154:157], v[176:179], v[50:53]
	s_setprio 0
	s_barrier
	s_add_i32 s30, 0, 0x18000
	s_add_i32 s31, 0, 0x1c000
	v_add_u32_e32 v142, s30, v184
	v_add_u32_e32 v172, s31, v184
	ds_read_b128 v[130:133], v142
	ds_read_b128 v[134:137], v142 offset:1024
	ds_read_b128 v[138:141], v142 offset:2048
	ds_read_b128 v[142:145], v142 offset:3072
	ds_read_b128 v[146:149], v172
	ds_read_b128 v[150:153], v172 offset:1024
	ds_read_b128 v[154:157], v172 offset:2048
	ds_read_b128 v[172:175], v172 offset:3072
	s_add_u32 s28, s78, 0x80000
	s_addc_u32 s29, s79, 0
	s_mov_b32 m0, s67
	v_lshl_add_u64 v[238:239], s[28:29], 0, v[158:159]
	ds_read_b128 v[176:179], v186 offset:32768
	ds_read_b128 v[180:183], v186 offset:33792
	ds_read_b128 v[188:191], v186 offset:34816
	ds_read_b128 v[192:195], v186 offset:35840
	ds_read_b128 v[196:199], v186 offset:36864
	ds_read_b128 v[200:203], v186 offset:37888
	ds_read_b128 v[204:207], v186 offset:38912
	ds_read_b128 v[208:211], v186 offset:39936
	global_load_lds_dwordx4 v[238:239], off
	v_lshl_add_u64 v[238:239], s[28:29], 0, v[162:163]
	s_mov_b32 m0, s72
	s_nop 0
	global_load_lds_dwordx4 v[238:239], off
	s_waitcnt vmcnt(8)
	s_waitcnt lgkmcnt(0)
	v_mfma_f32_16x16x32_bf16 v[126:129], v[130:133], v[176:179], v[126:129]
	v_mfma_f32_16x16x32_bf16 v[126:129], v[134:137], v[180:183], v[126:129]
	v_mfma_f32_16x16x32_bf16 v[110:113], v[134:137], v[192:195], v[110:113]
	v_mfma_f32_16x16x32_bf16 v[110:113], v[130:133], v[188:191], v[110:113]
	s_barrier
	s_setprio 1
	s_waitcnt lgkmcnt(0)
	v_mfma_f32_16x16x32_bf16 v[94:97], v[130:133], v[196:199], v[94:97]
	v_mfma_f32_16x16x32_bf16 v[94:97], v[134:137], v[200:203], v[94:97]
	v_mfma_f32_16x16x32_bf16 v[78:81], v[134:137], v[208:211], v[78:81]
	v_mfma_f32_16x16x32_bf16 v[78:81], v[130:133], v[204:207], v[78:81]
	v_mfma_f32_16x16x32_bf16 v[74:77], v[138:141], v[204:207], v[74:77]
	v_mfma_f32_16x16x32_bf16 v[74:77], v[142:145], v[208:211], v[74:77]
	v_mfma_f32_16x16x32_bf16 v[90:93], v[142:145], v[200:203], v[90:93]
	v_mfma_f32_16x16x32_bf16 v[90:93], v[138:141], v[196:199], v[90:93]
	v_mfma_f32_16x16x32_bf16 v[106:109], v[138:141], v[188:191], v[106:109]
	v_mfma_f32_16x16x32_bf16 v[106:109], v[142:145], v[192:195], v[106:109]
	v_mfma_f32_16x16x32_bf16 v[122:125], v[142:145], v[180:183], v[122:125]
	v_mfma_f32_16x16x32_bf16 v[122:125], v[138:141], v[176:179], v[122:125]
	s_setprio 0
	s_setprio 1
	v_mfma_f32_16x16x32_bf16 v[118:121], v[146:149], v[176:179], v[118:121]
	v_mfma_f32_16x16x32_bf16 v[118:121], v[150:153], v[180:183], v[118:121]
	v_mfma_f32_16x16x32_bf16 v[102:105], v[150:153], v[192:195], v[102:105]
	v_mfma_f32_16x16x32_bf16 v[102:105], v[146:149], v[188:191], v[102:105]
	v_mfma_f32_16x16x32_bf16 v[86:89], v[146:149], v[196:199], v[86:89]
	v_mfma_f32_16x16x32_bf16 v[86:89], v[150:153], v[200:203], v[86:89]
	v_mfma_f32_16x16x32_bf16 v[70:73], v[150:153], v[208:211], v[70:73]
	v_mfma_f32_16x16x32_bf16 v[70:73], v[146:149], v[204:207], v[70:73]
	v_mfma_f32_16x16x32_bf16 v[66:69], v[154:157], v[204:207], v[66:69]
	v_mfma_f32_16x16x32_bf16 v[66:69], v[172:175], v[208:211], v[66:69]
	v_mfma_f32_16x16x32_bf16 v[82:85], v[172:175], v[200:203], v[82:85]
	v_mfma_f32_16x16x32_bf16 v[82:85], v[154:157], v[196:199], v[82:85]
	v_mfma_f32_16x16x32_bf16 v[98:101], v[154:157], v[188:191], v[98:101]
	v_mfma_f32_16x16x32_bf16 v[98:101], v[172:175], v[192:195], v[98:101]
	v_mfma_f32_16x16x32_bf16 v[114:117], v[172:175], v[180:183], v[114:117]
	v_mfma_f32_16x16x32_bf16 v[114:117], v[154:157], v[176:179], v[114:117]
	s_setprio 0
	s_barrier
	s_add_i32 s28, s30, s11
	v_lshl_add_u64 v[212:213], v[212:213], 0, s[62:63]
	s_mov_b32 m0, s28
	ds_read_b128 v[176:179], v186 offset:49152
	ds_read_b128 v[180:183], v186 offset:50176
	ds_read_b128 v[188:191], v186 offset:51200
	ds_read_b128 v[192:195], v186 offset:52224
	ds_read_b128 v[196:199], v186 offset:53248
	ds_read_b128 v[200:203], v186 offset:54272
	ds_read_b128 v[204:207], v186 offset:55296
	ds_read_b128 v[208:211], v186 offset:56320
	global_load_lds_dwordx4 v[212:213], off
	s_add_i32 m0, s28, 0x2000
	s_add_u32 s28, s68, 0x80080
	v_lshl_add_u64 v[212:213], v[232:233], 0, s[62:63]
	s_addc_u32 s29, s69, 0
	s_add_i32 s30, s31, s11
	global_load_lds_dwordx4 v[212:213], off
	v_lshl_add_u64 v[212:213], s[28:29], 0, v[160:161]
	s_mov_b32 m0, s30
	s_nop 0
	global_load_lds_dwordx4 v[212:213], off
	v_lshl_add_u64 v[212:213], s[28:29], 0, v[164:165]
	s_add_i32 m0, s30, 0x2000
	s_nop 0
	global_load_lds_dwordx4 v[212:213], off
	v_lshl_add_u64 v[212:213], v[234:235], 0, s[62:63]
	s_mov_b32 m0, s18
	s_nop 0
	global_load_lds_dwordx4 v[212:213], off
	v_lshl_add_u64 v[212:213], v[236:237], 0, s[62:63]
	s_mov_b32 m0, s19
	s_nop 0
	global_load_lds_dwordx4 v[212:213], off
	s_waitcnt vmcnt(8)
	s_waitcnt lgkmcnt(0)
	v_mfma_f32_16x16x32_bf16 v[62:65], v[130:133], v[176:179], v[62:65]
	v_mfma_f32_16x16x32_bf16 v[62:65], v[134:137], v[180:183], v[62:65]
	v_mfma_f32_16x16x32_bf16 v[46:49], v[134:137], v[192:195], v[46:49]
	v_mfma_f32_16x16x32_bf16 v[46:49], v[130:133], v[188:191], v[46:49]
	s_barrier
	s_setprio 1
	s_waitcnt lgkmcnt(0)
	v_mfma_f32_16x16x32_bf16 v[30:33], v[130:133], v[196:199], v[30:33]
	v_mfma_f32_16x16x32_bf16 v[30:33], v[134:137], v[200:203], v[30:33]
	v_mfma_f32_16x16x32_bf16 v[14:17], v[134:137], v[208:211], v[14:17]
	v_mfma_f32_16x16x32_bf16 v[14:17], v[130:133], v[204:207], v[14:17]
	v_mfma_f32_16x16x32_bf16 v[10:13], v[138:141], v[204:207], v[10:13]
	v_mfma_f32_16x16x32_bf16 v[10:13], v[142:145], v[208:211], v[10:13]
	v_mfma_f32_16x16x32_bf16 v[26:29], v[142:145], v[200:203], v[26:29]
	v_mfma_f32_16x16x32_bf16 v[26:29], v[138:141], v[196:199], v[26:29]
	v_mfma_f32_16x16x32_bf16 v[42:45], v[138:141], v[188:191], v[42:45]
	v_mfma_f32_16x16x32_bf16 v[42:45], v[142:145], v[192:195], v[42:45]
	v_mfma_f32_16x16x32_bf16 v[58:61], v[142:145], v[180:183], v[58:61]
	v_mfma_f32_16x16x32_bf16 v[58:61], v[138:141], v[176:179], v[58:61]
	s_setprio 0
	s_setprio 1
	v_mfma_f32_16x16x32_bf16 v[54:57], v[146:149], v[176:179], v[54:57]
	v_mfma_f32_16x16x32_bf16 v[54:57], v[150:153], v[180:183], v[54:57]
	v_mfma_f32_16x16x32_bf16 v[38:41], v[150:153], v[192:195], v[38:41]
	v_mfma_f32_16x16x32_bf16 v[38:41], v[146:149], v[188:191], v[38:41]
	v_mfma_f32_16x16x32_bf16 v[22:25], v[146:149], v[196:199], v[22:25]
	v_mfma_f32_16x16x32_bf16 v[22:25], v[150:153], v[200:203], v[22:25]
	v_mfma_f32_16x16x32_bf16 v[6:9], v[150:153], v[208:211], v[6:9]
	v_mfma_f32_16x16x32_bf16 v[6:9], v[146:149], v[204:207], v[6:9]
	v_mfma_f32_16x16x32_bf16 v[2:5], v[154:157], v[204:207], v[2:5]
	v_mfma_f32_16x16x32_bf16 v[2:5], v[172:175], v[208:211], v[2:5]
	v_mfma_f32_16x16x32_bf16 v[18:21], v[172:175], v[200:203], v[18:21]
	v_mfma_f32_16x16x32_bf16 v[18:21], v[154:157], v[196:199], v[18:21]
	v_mfma_f32_16x16x32_bf16 v[34:37], v[154:157], v[188:191], v[34:37]
	v_mfma_f32_16x16x32_bf16 v[34:37], v[172:175], v[192:195], v[34:37]
	v_mfma_f32_16x16x32_bf16 v[50:53], v[172:175], v[180:183], v[50:53]
	v_mfma_f32_16x16x32_bf16 v[50:53], v[154:157], v[176:179], v[50:53]
	s_setprio 0
	s_barrier
	s_add_i32 s27, s27, 2
	s_add_u32 s54, s54, 0x100
	s_addc_u32 s55, s55, 0
	s_add_u32 s25, s25, 0x100
	s_addc_u32 s26, s26, 0
	s_cmp_gt_u32 s27, 29
	s_cbranch_scc0 .LBB0_32
	s_and_b64 vcc, exec, s[2:3]
	s_cbranch_vccz .LBB0_35
	s_barrier

.LBB0_132:
	s_add_u32 s23, s48, 0xfff80080
	s_addc_u32 s24, s49, -1
	s_add_i32 s25, 0, 0x10000
	s_cmp_eq_u32 s22, 28
	s_cselect_b32 s69, s3, s24
	s_cselect_b32 s68, s18, s23
	s_cselect_b32 s51, s1, s21
	s_cselect_b32 s50, s19, s20
	s_add_i32 s23, 0, 0x14000
	v_add_u32_e32 v156, s25, v165
	v_add_u32_e32 v169, s23, v165
	ds_read_b128 v[144:147], v156
	ds_read_b128 v[148:151], v156 offset:1024
	ds_read_b128 v[152:155], v156 offset:2048
	ds_read_b128 v[156:159], v156 offset:3072
	ds_read_b128 v[160:163], v169
	ds_read_b128 v[170:173], v169 offset:1024
	ds_read_b128 v[174:177], v169 offset:2048
	ds_read_b128 v[178:181], v169 offset:3072
	v_lshl_add_u64 v[232:233], s[48:49], 0, v[140:141]
	s_add_i32 m0, s45, 0xc000
	ds_read_b128 v[182:185], v168
	ds_read_b128 v[186:189], v168 offset:1024
	ds_read_b128 v[190:193], v168 offset:2048
	ds_read_b128 v[194:197], v168 offset:3072
	ds_read_b128 v[198:201], v168 offset:4096
	ds_read_b128 v[202:205], v168 offset:5120
	ds_read_b128 v[206:209], v168 offset:6144
	ds_read_b128 v[210:213], v168 offset:7168
	global_load_lds_dwordx4 v[232:233], off
	v_lshl_add_u64 v[232:233], s[48:49], 0, v[142:143]
	s_add_i32 m0, s45, 0xe000
	s_nop 0
	global_load_lds_dwordx4 v[232:233], off
	s_waitcnt vmcnt(8)
	s_waitcnt lgkmcnt(0)
	v_mfma_f32_16x16x32_bf16 v[126:129], v[144:147], v[182:185], v[126:129]
	v_mfma_f32_16x16x32_bf16 v[126:129], v[148:151], v[186:189], v[126:129]
	v_mfma_f32_16x16x32_bf16 v[110:113], v[148:151], v[194:197], v[110:113]
	v_mfma_f32_16x16x32_bf16 v[110:113], v[144:147], v[190:193], v[110:113]
	s_barrier
	s_setprio 1
	s_waitcnt lgkmcnt(0)
	v_mfma_f32_16x16x32_bf16 v[102:105], v[144:147], v[198:201], v[102:105]
	v_mfma_f32_16x16x32_bf16 v[102:105], v[148:151], v[202:205], v[102:105]
	v_mfma_f32_16x16x32_bf16 v[86:89], v[148:151], v[210:213], v[86:89]
	v_mfma_f32_16x16x32_bf16 v[86:89], v[144:147], v[206:209], v[86:89]
	v_mfma_f32_16x16x32_bf16 v[78:81], v[152:155], v[206:209], v[78:81]
	v_mfma_f32_16x16x32_bf16 v[78:81], v[156:159], v[210:213], v[78:81]
	v_mfma_f32_16x16x32_bf16 v[94:97], v[156:159], v[202:205], v[94:97]
	v_mfma_f32_16x16x32_bf16 v[94:97], v[152:155], v[198:201], v[94:97]
	v_mfma_f32_16x16x32_bf16 v[106:109], v[152:155], v[190:193], v[106:109]
	v_mfma_f32_16x16x32_bf16 v[106:109], v[156:159], v[194:197], v[106:109]
	v_mfma_f32_16x16x32_bf16 v[122:125], v[156:159], v[186:189], v[122:125]
	v_mfma_f32_16x16x32_bf16 v[122:125], v[152:155], v[182:185], v[122:125]
	s_setprio 0
	s_setprio 1
	v_mfma_f32_16x16x32_bf16 v[118:121], v[160:163], v[182:185], v[118:121]
	v_mfma_f32_16x16x32_bf16 v[118:121], v[170:173], v[186:189], v[118:121]
	v_mfma_f32_16x16x32_bf16 v[98:101], v[170:173], v[194:197], v[98:101]
	v_mfma_f32_16x16x32_bf16 v[98:101], v[160:163], v[190:193], v[98:101]
	v_mfma_f32_16x16x32_bf16 v[82:85], v[160:163], v[198:201], v[82:85]
	v_mfma_f32_16x16x32_bf16 v[82:85], v[170:173], v[202:205], v[82:85]
	v_mfma_f32_16x16x32_bf16 v[70:73], v[170:173], v[210:213], v[70:73]
	v_mfma_f32_16x16x32_bf16 v[70:73], v[160:163], v[206:209], v[70:73]
	v_mfma_f32_16x16x32_bf16 v[66:69], v[174:177], v[206:209], v[66:69]
	v_mfma_f32_16x16x32_bf16 v[66:69], v[178:181], v[210:213], v[66:69]
	v_mfma_f32_16x16x32_bf16 v[74:77], v[178:181], v[202:205], v[74:77]
	v_mfma_f32_16x16x32_bf16 v[74:77], v[174:177], v[198:201], v[74:77]
	v_mfma_f32_16x16x32_bf16 v[90:93], v[174:177], v[190:193], v[90:93]
	v_mfma_f32_16x16x32_bf16 v[90:93], v[178:181], v[194:197], v[90:93]
	v_mfma_f32_16x16x32_bf16 v[114:117], v[178:181], v[186:189], v[114:117]
	v_mfma_f32_16x16x32_bf16 v[114:117], v[174:177], v[182:185], v[114:117]
	s_setprio 0
	s_barrier
	s_add_i32 s24, s25, s16
	v_lshl_add_u64 v[232:233], s[50:51], 0, v[132:133]
	s_mov_b32 m0, s24
	ds_read_b128 v[182:185], v168 offset:16384
	ds_read_b128 v[186:189], v168 offset:17408
	ds_read_b128 v[190:193], v168 offset:18432
	ds_read_b128 v[194:197], v168 offset:19456
	ds_read_b128 v[198:201], v168 offset:20480
	ds_read_b128 v[202:205], v168 offset:21504
	ds_read_b128 v[206:209], v168 offset:22528
	ds_read_b128 v[210:213], v168 offset:23552
	global_load_lds_dwordx4 v[232:233], off
	s_add_i32 m0, s24, 0x2000
	s_add_u32 s24, s50, 0x80000
	v_lshl_add_u64 v[234:235], s[50:51], 0, v[136:137]
	s_addc_u32 s25, s51, 0
	s_add_i32 s23, s23, s16
	global_load_lds_dwordx4 v[234:235], off
	v_lshl_add_u64 v[236:237], s[24:25], 0, v[132:133]
	s_mov_b32 m0, s23
	v_lshl_add_u64 v[238:239], s[68:69], 0, v[134:135]
	global_load_lds_dwordx4 v[236:237], off
	v_lshl_add_u64 v[236:237], s[24:25], 0, v[136:137]
	s_add_i32 m0, s23, 0x2000
	s_nop 0
	global_load_lds_dwordx4 v[236:237], off
	v_lshl_add_u64 v[236:237], s[68:69], 0, v[130:131]
	s_mov_b32 m0, s45
	s_nop 0
	global_load_lds_dwordx4 v[236:237], off
	s_mov_b32 m0, s57
	s_nop 0
	global_load_lds_dwordx4 v[238:239], off
	s_waitcnt vmcnt(8)
	s_waitcnt lgkmcnt(0)
	v_mfma_f32_16x16x32_bf16 v[62:65], v[144:147], v[182:185], v[62:65]
	v_mfma_f32_16x16x32_bf16 v[62:65], v[148:151], v[186:189], v[62:65]
	v_mfma_f32_16x16x32_bf16 v[54:57], v[148:151], v[194:197], v[54:57]
	v_mfma_f32_16x16x32_bf16 v[54:57], v[144:147], v[190:193], v[54:57]
	s_barrier
	s_setprio 1
	s_waitcnt lgkmcnt(0)
	v_mfma_f32_16x16x32_bf16 v[38:41], v[144:147], v[198:201], v[38:41]
	v_mfma_f32_16x16x32_bf16 v[38:41], v[148:151], v[202:205], v[38:41]
	v_mfma_f32_16x16x32_bf16 v[22:25], v[148:151], v[210:213], v[22:25]
	v_mfma_f32_16x16x32_bf16 v[22:25], v[144:147], v[206:209], v[22:25]
	v_mfma_f32_16x16x32_bf16 v[14:17], v[152:155], v[206:209], v[14:17]
	v_mfma_f32_16x16x32_bf16 v[14:17], v[156:159], v[210:213], v[14:17]
	v_mfma_f32_16x16x32_bf16 v[30:33], v[156:159], v[202:205], v[30:33]
	v_mfma_f32_16x16x32_bf16 v[30:33], v[152:155], v[198:201], v[30:33]
	v_mfma_f32_16x16x32_bf16 v[46:49], v[152:155], v[190:193], v[46:49]
	v_mfma_f32_16x16x32_bf16 v[46:49], v[156:159], v[194:197], v[46:49]
	v_mfma_f32_16x16x32_bf16 v[58:61], v[156:159], v[186:189], v[58:61]
	v_mfma_f32_16x16x32_bf16 v[58:61], v[152:155], v[182:185], v[58:61]
	s_setprio 0
	s_setprio 1
	v_mfma_f32_16x16x32_bf16 v[50:53], v[160:163], v[182:185], v[50:53]
	v_mfma_f32_16x16x32_bf16 v[50:53], v[170:173], v[186:189], v[50:53]
	v_mfma_f32_16x16x32_bf16 v[34:37], v[170:173], v[194:197], v[34:37]
	v_mfma_f32_16x16x32_bf16 v[34:37], v[160:163], v[190:193], v[34:37]
	v_mfma_f32_16x16x32_bf16 v[18:21], v[160:163], v[198:201], v[18:21]
	v_mfma_f32_16x16x32_bf16 v[18:21], v[170:173], v[202:205], v[18:21]
	v_mfma_f32_16x16x32_bf16 v[6:9], v[170:173], v[210:213], v[6:9]
	v_mfma_f32_16x16x32_bf16 v[6:9], v[160:163], v[206:209], v[6:9]
	v_mfma_f32_16x16x32_bf16 v[2:5], v[174:177], v[206:209], v[2:5]
	v_mfma_f32_16x16x32_bf16 v[2:5], v[178:181], v[210:213], v[2:5]
	v_mfma_f32_16x16x32_bf16 v[10:13], v[178:181], v[202:205], v[10:13]
	v_mfma_f32_16x16x32_bf16 v[10:13], v[174:177], v[198:201], v[10:13]
	v_mfma_f32_16x16x32_bf16 v[26:29], v[174:177], v[190:193], v[26:29]
	v_mfma_f32_16x16x32_bf16 v[26:29], v[178:181], v[194:197], v[26:29]
	v_mfma_f32_16x16x32_bf16 v[42:45], v[178:181], v[186:189], v[42:45]
	v_mfma_f32_16x16x32_bf16 v[42:45], v[174:177], v[182:185], v[42:45]
	s_setprio 0
	s_barrier
	s_add_i32 s23, 0, 0x18000
	s_add_i32 s26, 0, 0x1c000
	v_add_u32_e32 v156, s23, v165
	v_add_u32_e32 v169, s26, v165
	ds_read_b128 v[144:147], v156
	ds_read_b128 v[148:151], v156 offset:1024
	ds_read_b128 v[152:155], v156 offset:2048
	ds_read_b128 v[156:159], v156 offset:3072
	ds_read_b128 v[160:163], v169
	ds_read_b128 v[170:173], v169 offset:1024
	ds_read_b128 v[174:177], v169 offset:2048
	ds_read_b128 v[178:181], v169 offset:3072
	s_add_u32 s24, s68, 0x80000
	s_addc_u32 s25, s69, 0
	s_mov_b32 m0, s42
	v_lshl_add_u64 v[240:241], s[24:25], 0, v[130:131]
	ds_read_b128 v[182:185], v168 offset:32768
	ds_read_b128 v[186:189], v168 offset:33792
	ds_read_b128 v[190:193], v168 offset:34816
	ds_read_b128 v[194:197], v168 offset:35840
	ds_read_b128 v[198:201], v168 offset:36864
	ds_read_b128 v[202:205], v168 offset:37888
	ds_read_b128 v[206:209], v168 offset:38912
	ds_read_b128 v[210:213], v168 offset:39936
	global_load_lds_dwordx4 v[240:241], off
	v_lshl_add_u64 v[240:241], s[24:25], 0, v[134:135]
	s_mov_b32 m0, s6
	s_nop 0
	global_load_lds_dwordx4 v[240:241], off
	s_waitcnt vmcnt(8)
	s_waitcnt lgkmcnt(0)
	v_mfma_f32_16x16x32_bf16 v[126:129], v[144:147], v[182:185], v[126:129]
	v_mfma_f32_16x16x32_bf16 v[126:129], v[148:151], v[186:189], v[126:129]
	v_mfma_f32_16x16x32_bf16 v[110:113], v[148:151], v[194:197], v[110:113]
	v_mfma_f32_16x16x32_bf16 v[110:113], v[144:147], v[190:193], v[110:113]
	s_barrier
	s_setprio 1
	s_waitcnt lgkmcnt(0)
	v_mfma_f32_16x16x32_bf16 v[102:105], v[144:147], v[198:201], v[102:105]
	v_mfma_f32_16x16x32_bf16 v[102:105], v[148:151], v[202:205], v[102:105]
	v_mfma_f32_16x16x32_bf16 v[86:89], v[148:151], v[210:213], v[86:89]
	v_mfma_f32_16x16x32_bf16 v[86:89], v[144:147], v[206:209], v[86:89]
	v_mfma_f32_16x16x32_bf16 v[78:81], v[152:155], v[206:209], v[78:81]
	v_mfma_f32_16x16x32_bf16 v[78:81], v[156:159], v[210:213], v[78:81]
	v_mfma_f32_16x16x32_bf16 v[94:97], v[156:159], v[202:205], v[94:97]
	v_mfma_f32_16x16x32_bf16 v[94:97], v[152:155], v[198:201], v[94:97]
	v_mfma_f32_16x16x32_bf16 v[106:109], v[152:155], v[190:193], v[106:109]
	v_mfma_f32_16x16x32_bf16 v[106:109], v[156:159], v[194:197], v[106:109]
	v_mfma_f32_16x16x32_bf16 v[122:125], v[156:159], v[186:189], v[122:125]
	v_mfma_f32_16x16x32_bf16 v[122:125], v[152:155], v[182:185], v[122:125]
	s_setprio 0
	s_setprio 1
	v_mfma_f32_16x16x32_bf16 v[118:121], v[160:163], v[182:185], v[118:121]
	v_mfma_f32_16x16x32_bf16 v[118:121], v[170:173], v[186:189], v[118:121]
	v_mfma_f32_16x16x32_bf16 v[98:101], v[170:173], v[194:197], v[98:101]
	v_mfma_f32_16x16x32_bf16 v[98:101], v[160:163], v[190:193], v[98:101]
	v_mfma_f32_16x16x32_bf16 v[82:85], v[160:163], v[198:201], v[82:85]
	v_mfma_f32_16x16x32_bf16 v[82:85], v[170:173], v[202:205], v[82:85]
	v_mfma_f32_16x16x32_bf16 v[70:73], v[170:173], v[210:213], v[70:73]
	v_mfma_f32_16x16x32_bf16 v[70:73], v[160:163], v[206:209], v[70:73]
	v_mfma_f32_16x16x32_bf16 v[66:69], v[174:177], v[206:209], v[66:69]
	v_mfma_f32_16x16x32_bf16 v[66:69], v[178:181], v[210:213], v[66:69]
	v_mfma_f32_16x16x32_bf16 v[74:77], v[178:181], v[202:205], v[74:77]
	v_mfma_f32_16x16x32_bf16 v[74:77], v[174:177], v[198:201], v[74:77]
	v_mfma_f32_16x16x32_bf16 v[90:93], v[174:177], v[190:193], v[90:93]
	v_mfma_f32_16x16x32_bf16 v[90:93], v[178:181], v[194:197], v[90:93]
	v_mfma_f32_16x16x32_bf16 v[114:117], v[178:181], v[186:189], v[114:117]
	v_mfma_f32_16x16x32_bf16 v[114:117], v[174:177], v[182:185], v[114:117]
	s_setprio 0
	s_barrier
	s_add_i32 s23, s23, s16
	v_lshl_add_u64 v[232:233], v[232:233], 0, s[62:63]
	s_mov_b32 m0, s23
	ds_read_b128 v[182:185], v168 offset:49152
	ds_read_b128 v[186:189], v168 offset:50176
	ds_read_b128 v[190:193], v168 offset:51200
	ds_read_b128 v[194:197], v168 offset:52224
	ds_read_b128 v[198:201], v168 offset:53248
	ds_read_b128 v[202:205], v168 offset:54272
	ds_read_b128 v[206:209], v168 offset:55296
	ds_read_b128 v[210:213], v168 offset:56320
	global_load_lds_dwordx4 v[232:233], off
	s_add_i32 m0, s23, 0x2000
	s_add_u32 s24, s50, 0x80080
	v_lshl_add_u64 v[232:233], v[234:235], 0, s[62:63]
	s_addc_u32 s25, s51, 0
	s_add_i32 s23, s26, s16
	global_load_lds_dwordx4 v[232:233], off
	v_lshl_add_u64 v[232:233], s[24:25], 0, v[132:133]
	s_mov_b32 m0, s23
	s_nop 0
	global_load_lds_dwordx4 v[232:233], off
	v_lshl_add_u64 v[232:233], s[24:25], 0, v[136:137]
	s_add_i32 m0, s23, 0x2000
	s_nop 0
	global_load_lds_dwordx4 v[232:233], off
	v_lshl_add_u64 v[232:233], v[236:237], 0, s[62:63]
	s_mov_b32 m0, s76
	s_nop 0
	global_load_lds_dwordx4 v[232:233], off
	v_lshl_add_u64 v[232:233], v[238:239], 0, s[62:63]
	s_mov_b32 m0, s77
	s_nop 0
	global_load_lds_dwordx4 v[232:233], off
	s_waitcnt vmcnt(8)
	s_waitcnt lgkmcnt(0)
	v_mfma_f32_16x16x32_bf16 v[62:65], v[144:147], v[182:185], v[62:65]
	v_mfma_f32_16x16x32_bf16 v[62:65], v[148:151], v[186:189], v[62:65]
	v_mfma_f32_16x16x32_bf16 v[54:57], v[148:151], v[194:197], v[54:57]
	v_mfma_f32_16x16x32_bf16 v[54:57], v[144:147], v[190:193], v[54:57]
	s_barrier
	s_setprio 1
	s_waitcnt lgkmcnt(0)
	v_mfma_f32_16x16x32_bf16 v[38:41], v[144:147], v[198:201], v[38:41]
	v_mfma_f32_16x16x32_bf16 v[38:41], v[148:151], v[202:205], v[38:41]
	v_mfma_f32_16x16x32_bf16 v[22:25], v[148:151], v[210:213], v[22:25]
	v_mfma_f32_16x16x32_bf16 v[22:25], v[144:147], v[206:209], v[22:25]
	v_mfma_f32_16x16x32_bf16 v[14:17], v[152:155], v[206:209], v[14:17]
	v_mfma_f32_16x16x32_bf16 v[14:17], v[156:159], v[210:213], v[14:17]
	v_mfma_f32_16x16x32_bf16 v[30:33], v[156:159], v[202:205], v[30:33]
	v_mfma_f32_16x16x32_bf16 v[30:33], v[152:155], v[198:201], v[30:33]
	v_mfma_f32_16x16x32_bf16 v[46:49], v[152:155], v[190:193], v[46:49]
	v_mfma_f32_16x16x32_bf16 v[46:49], v[156:159], v[194:197], v[46:49]
	v_mfma_f32_16x16x32_bf16 v[58:61], v[156:159], v[186:189], v[58:61]
	v_mfma_f32_16x16x32_bf16 v[58:61], v[152:155], v[182:185], v[58:61]
	s_setprio 0
	s_setprio 1
	v_mfma_f32_16x16x32_bf16 v[50:53], v[160:163], v[182:185], v[50:53]
	v_mfma_f32_16x16x32_bf16 v[50:53], v[170:173], v[186:189], v[50:53]
	v_mfma_f32_16x16x32_bf16 v[34:37], v[170:173], v[194:197], v[34:37]
	v_mfma_f32_16x16x32_bf16 v[34:37], v[160:163], v[190:193], v[34:37]
	v_mfma_f32_16x16x32_bf16 v[18:21], v[160:163], v[198:201], v[18:21]
	v_mfma_f32_16x16x32_bf16 v[18:21], v[170:173], v[202:205], v[18:21]
	v_mfma_f32_16x16x32_bf16 v[6:9], v[170:173], v[210:213], v[6:9]
	v_mfma_f32_16x16x32_bf16 v[6:9], v[160:163], v[206:209], v[6:9]
	v_mfma_f32_16x16x32_bf16 v[2:5], v[174:177], v[206:209], v[2:5]
	v_mfma_f32_16x16x32_bf16 v[2:5], v[178:181], v[210:213], v[2:5]
	v_mfma_f32_16x16x32_bf16 v[10:13], v[178:181], v[202:205], v[10:13]
	v_mfma_f32_16x16x32_bf16 v[10:13], v[174:177], v[198:201], v[10:13]
	v_mfma_f32_16x16x32_bf16 v[26:29], v[174:177], v[190:193], v[26:29]
	v_mfma_f32_16x16x32_bf16 v[26:29], v[178:181], v[194:197], v[26:29]
	v_mfma_f32_16x16x32_bf16 v[42:45], v[178:181], v[186:189], v[42:45]
	v_mfma_f32_16x16x32_bf16 v[42:45], v[174:177], v[182:185], v[42:45]
	s_setprio 0
	s_barrier
	s_add_i32 s22, s22, 2
	s_add_u32 s48, s48, 0x100
	s_addc_u32 s49, s49, 0
	s_add_u32 s20, s20, 0x100
	s_addc_u32 s21, s21, 0
	s_cmp_gt_u32 s22, 29
	s_cbranch_scc0 .LBB0_132
	s_and_b64 vcc, exec, s[10:11]
	s_cbranch_vccz .LBB0_135
	s_barrier

.LBB0_238:
	s_add_u32 s10, s12, 0x100
	s_addc_u32 s11, s13, 0
	s_add_i32 s23, 0, 0x10000
	s_cmpk_eq_i32 s22, 0x52
	s_cselect_b32 vcc_hi, s47, s11
	s_cselect_b32 vcc_lo, s46, s10
	s_cselect_b32 s51, s49, s21
	s_cselect_b32 s50, s48, s20
	s_add_i32 s24, 0, 0x14000
	v_add_u32_e32 v142, s23, v194
	v_add_u32_e32 v158, s24, v194
	ds_read_b128 v[122:125], v142
	ds_read_b128 v[126:129], v142 offset:1024
	ds_read_b128 v[138:141], v142 offset:2048
	ds_read_b128 v[142:145], v142 offset:3072
	ds_read_b128 v[146:149], v158
	ds_read_b128 v[150:153], v158 offset:1024
	ds_read_b128 v[154:157], v158 offset:2048
	ds_read_b128 v[158:161], v158 offset:3072
	v_lshl_add_u64 v[212:213], s[12:13], 0, v[170:171]
	s_add_i32 m0, s57, 0xc000
	ds_read_b128 v[174:177], v198
	ds_read_b128 v[178:181], v198 offset:1024
	ds_read_b128 v[182:185], v198 offset:2048
	ds_read_b128 v[186:189], v198 offset:3072
	ds_read_b128 v[190:193], v198 offset:4096
	ds_read_b128 v[200:203], v198 offset:5120
	ds_read_b128 v[204:207], v198 offset:6144
	ds_read_b128 v[208:211], v198 offset:7168
	global_load_lds_dwordx4 v[212:213], off
	v_lshl_add_u64 v[212:213], s[12:13], 0, v[172:173]
	s_add_i32 m0, s57, 0xe000
	s_nop 0
	global_load_lds_dwordx4 v[212:213], off
	s_waitcnt vmcnt(8)
	s_waitcnt lgkmcnt(0)
	v_mfma_f32_16x16x32_bf16 v[134:137], v[122:125], v[174:177], v[134:137]
	v_mfma_f32_16x16x32_bf16 v[134:137], v[126:129], v[178:181], v[134:137]
	v_mfma_f32_16x16x32_bf16 v[110:113], v[126:129], v[186:189], v[110:113]
	v_mfma_f32_16x16x32_bf16 v[110:113], v[122:125], v[182:185], v[110:113]
	s_barrier
	s_setprio 1
	s_waitcnt lgkmcnt(0)
	v_mfma_f32_16x16x32_bf16 v[94:97], v[122:125], v[190:193], v[94:97]
	v_mfma_f32_16x16x32_bf16 v[94:97], v[126:129], v[200:203], v[94:97]
	v_mfma_f32_16x16x32_bf16 v[78:81], v[126:129], v[208:211], v[78:81]
	v_mfma_f32_16x16x32_bf16 v[78:81], v[122:125], v[204:207], v[78:81]
	v_mfma_f32_16x16x32_bf16 v[74:77], v[138:141], v[204:207], v[74:77]
	v_mfma_f32_16x16x32_bf16 v[74:77], v[142:145], v[208:211], v[74:77]
	v_mfma_f32_16x16x32_bf16 v[90:93], v[142:145], v[200:203], v[90:93]
	v_mfma_f32_16x16x32_bf16 v[90:93], v[138:141], v[190:193], v[90:93]
	v_mfma_f32_16x16x32_bf16 v[106:109], v[138:141], v[182:185], v[106:109]
	v_mfma_f32_16x16x32_bf16 v[106:109], v[142:145], v[186:189], v[106:109]
	v_mfma_f32_16x16x32_bf16 v[130:133], v[142:145], v[178:181], v[130:133]
	v_mfma_f32_16x16x32_bf16 v[130:133], v[138:141], v[174:177], v[130:133]
	s_setprio 0
	s_setprio 1
	v_mfma_f32_16x16x32_bf16 v[118:121], v[146:149], v[174:177], v[118:121]
	v_mfma_f32_16x16x32_bf16 v[118:121], v[150:153], v[178:181], v[118:121]
	v_mfma_f32_16x16x32_bf16 v[102:105], v[150:153], v[186:189], v[102:105]
	v_mfma_f32_16x16x32_bf16 v[102:105], v[146:149], v[182:185], v[102:105]
	v_mfma_f32_16x16x32_bf16 v[86:89], v[146:149], v[190:193], v[86:89]
	v_mfma_f32_16x16x32_bf16 v[86:89], v[150:153], v[200:203], v[86:89]
	v_mfma_f32_16x16x32_bf16 v[70:73], v[150:153], v[208:211], v[70:73]
	v_mfma_f32_16x16x32_bf16 v[70:73], v[146:149], v[204:207], v[70:73]
	v_mfma_f32_16x16x32_bf16 v[66:69], v[154:157], v[204:207], v[66:69]
	v_mfma_f32_16x16x32_bf16 v[66:69], v[158:161], v[208:211], v[66:69]
	v_mfma_f32_16x16x32_bf16 v[82:85], v[158:161], v[200:203], v[82:85]
	v_mfma_f32_16x16x32_bf16 v[82:85], v[154:157], v[190:193], v[82:85]
	v_mfma_f32_16x16x32_bf16 v[98:101], v[154:157], v[182:185], v[98:101]
	v_mfma_f32_16x16x32_bf16 v[98:101], v[158:161], v[186:189], v[98:101]
	v_mfma_f32_16x16x32_bf16 v[114:117], v[158:161], v[178:181], v[114:117]
	v_mfma_f32_16x16x32_bf16 v[114:117], v[154:157], v[174:177], v[114:117]
	s_setprio 0
	s_barrier
	s_add_i32 s12, s23, s42
	v_lshl_add_u64 v[212:213], s[50:51], 0, v[164:165]
	s_mov_b32 m0, s12
	ds_read_b128 v[174:177], v198 offset:16384
	ds_read_b128 v[178:181], v198 offset:17408
	ds_read_b128 v[182:185], v198 offset:18432
	ds_read_b128 v[186:189], v198 offset:19456
	ds_read_b128 v[190:193], v198 offset:20480
	ds_read_b128 v[200:203], v198 offset:21504
	ds_read_b128 v[204:207], v198 offset:22528
	ds_read_b128 v[208:211], v198 offset:23552
	global_load_lds_dwordx4 v[212:213], off
	s_add_i32 m0, s12, 0x2000
	s_add_u32 s12, s50, 0x158000
	v_lshl_add_u64 v[232:233], s[50:51], 0, v[168:169]
	s_addc_u32 s13, s51, 0
	s_add_i32 s23, s24, s42
	global_load_lds_dwordx4 v[232:233], off
	v_lshl_add_u64 v[234:235], s[12:13], 0, v[164:165]
	s_mov_b32 m0, s23
	v_lshl_add_u64 v[236:237], vcc, 0, v[166:167]
	global_load_lds_dwordx4 v[234:235], off
	v_lshl_add_u64 v[234:235], s[12:13], 0, v[168:169]
	s_add_i32 m0, s23, 0x2000
	s_nop 0
	global_load_lds_dwordx4 v[234:235], off
	v_lshl_add_u64 v[234:235], vcc, 0, v[162:163]
	s_mov_b32 m0, s57
	s_nop 0
	global_load_lds_dwordx4 v[234:235], off
	s_mov_b32 m0, s58
	s_nop 0
	global_load_lds_dwordx4 v[236:237], off
	s_waitcnt vmcnt(8)
	s_waitcnt lgkmcnt(0)
	v_mfma_f32_16x16x32_bf16 v[62:65], v[122:125], v[174:177], v[62:65]
	v_mfma_f32_16x16x32_bf16 v[62:65], v[126:129], v[178:181], v[62:65]
	v_mfma_f32_16x16x32_bf16 v[46:49], v[126:129], v[186:189], v[46:49]
	v_mfma_f32_16x16x32_bf16 v[46:49], v[122:125], v[182:185], v[46:49]
	s_barrier
	s_setprio 1
	s_waitcnt lgkmcnt(0)
	v_mfma_f32_16x16x32_bf16 v[30:33], v[122:125], v[190:193], v[30:33]
	v_mfma_f32_16x16x32_bf16 v[30:33], v[126:129], v[200:203], v[30:33]
	v_mfma_f32_16x16x32_bf16 v[14:17], v[126:129], v[208:211], v[14:17]
	v_mfma_f32_16x16x32_bf16 v[14:17], v[122:125], v[204:207], v[14:17]
	v_mfma_f32_16x16x32_bf16 v[10:13], v[138:141], v[204:207], v[10:13]
	v_mfma_f32_16x16x32_bf16 v[10:13], v[142:145], v[208:211], v[10:13]
	v_mfma_f32_16x16x32_bf16 v[26:29], v[142:145], v[200:203], v[26:29]
	v_mfma_f32_16x16x32_bf16 v[26:29], v[138:141], v[190:193], v[26:29]
	v_mfma_f32_16x16x32_bf16 v[42:45], v[138:141], v[182:185], v[42:45]
	v_mfma_f32_16x16x32_bf16 v[42:45], v[142:145], v[186:189], v[42:45]
	v_mfma_f32_16x16x32_bf16 v[58:61], v[142:145], v[178:181], v[58:61]
	v_mfma_f32_16x16x32_bf16 v[58:61], v[138:141], v[174:177], v[58:61]
	s_setprio 0
	s_setprio 1
	v_mfma_f32_16x16x32_bf16 v[54:57], v[146:149], v[174:177], v[54:57]
	v_mfma_f32_16x16x32_bf16 v[54:57], v[150:153], v[178:181], v[54:57]
	v_mfma_f32_16x16x32_bf16 v[38:41], v[150:153], v[186:189], v[38:41]
	v_mfma_f32_16x16x32_bf16 v[38:41], v[146:149], v[182:185], v[38:41]
	v_mfma_f32_16x16x32_bf16 v[22:25], v[146:149], v[190:193], v[22:25]
	v_mfma_f32_16x16x32_bf16 v[22:25], v[150:153], v[200:203], v[22:25]
	v_mfma_f32_16x16x32_bf16 v[6:9], v[150:153], v[208:211], v[6:9]
	v_mfma_f32_16x16x32_bf16 v[6:9], v[146:149], v[204:207], v[6:9]
	v_mfma_f32_16x16x32_bf16 v[2:5], v[154:157], v[204:207], v[2:5]
	v_mfma_f32_16x16x32_bf16 v[2:5], v[158:161], v[208:211], v[2:5]
	v_mfma_f32_16x16x32_bf16 v[18:21], v[158:161], v[200:203], v[18:21]
	v_mfma_f32_16x16x32_bf16 v[18:21], v[154:157], v[190:193], v[18:21]
	v_mfma_f32_16x16x32_bf16 v[34:37], v[154:157], v[182:185], v[34:37]
	v_mfma_f32_16x16x32_bf16 v[34:37], v[158:161], v[186:189], v[34:37]
	v_mfma_f32_16x16x32_bf16 v[50:53], v[158:161], v[178:181], v[50:53]
	v_mfma_f32_16x16x32_bf16 v[50:53], v[154:157], v[174:177], v[50:53]
	s_setprio 0
	s_barrier
	s_add_i32 s23, 0, 0x18000
	s_add_i32 s24, 0, 0x1c000
	v_add_u32_e32 v142, s23, v194
	v_add_u32_e32 v158, s24, v194
	ds_read_b128 v[122:125], v142
	ds_read_b128 v[126:129], v142 offset:1024
	ds_read_b128 v[138:141], v142 offset:2048
	ds_read_b128 v[142:145], v142 offset:3072
	ds_read_b128 v[146:149], v158
	ds_read_b128 v[150:153], v158 offset:1024
	ds_read_b128 v[154:157], v158 offset:2048
	ds_read_b128 v[158:161], v158 offset:3072
	s_add_u32 s12, vcc_lo, 0x158000
	s_addc_u32 s13, vcc_hi, 0
	s_mov_b32 m0, s67
	v_lshl_add_u64 v[238:239], s[12:13], 0, v[162:163]
	ds_read_b128 v[174:177], v198 offset:32768
	ds_read_b128 v[178:181], v198 offset:33792
	ds_read_b128 v[182:185], v198 offset:34816
	ds_read_b128 v[186:189], v198 offset:35840
	ds_read_b128 v[190:193], v198 offset:36864
	ds_read_b128 v[200:203], v198 offset:37888
	ds_read_b128 v[204:207], v198 offset:38912
	ds_read_b128 v[208:211], v198 offset:39936
	global_load_lds_dwordx4 v[238:239], off
	v_lshl_add_u64 v[238:239], s[12:13], 0, v[166:167]
	s_mov_b32 m0, s76
	s_nop 0
	global_load_lds_dwordx4 v[238:239], off
	s_waitcnt vmcnt(8)
	s_waitcnt lgkmcnt(0)
	v_mfma_f32_16x16x32_bf16 v[134:137], v[122:125], v[174:177], v[134:137]
	v_mfma_f32_16x16x32_bf16 v[134:137], v[126:129], v[178:181], v[134:137]
	v_mfma_f32_16x16x32_bf16 v[110:113], v[126:129], v[186:189], v[110:113]
	v_mfma_f32_16x16x32_bf16 v[110:113], v[122:125], v[182:185], v[110:113]
	s_barrier
	s_setprio 1
	s_waitcnt lgkmcnt(0)
	v_mfma_f32_16x16x32_bf16 v[94:97], v[122:125], v[190:193], v[94:97]
	v_mfma_f32_16x16x32_bf16 v[94:97], v[126:129], v[200:203], v[94:97]
	v_mfma_f32_16x16x32_bf16 v[78:81], v[126:129], v[208:211], v[78:81]
	v_mfma_f32_16x16x32_bf16 v[78:81], v[122:125], v[204:207], v[78:81]
	v_mfma_f32_16x16x32_bf16 v[74:77], v[138:141], v[204:207], v[74:77]
	v_mfma_f32_16x16x32_bf16 v[74:77], v[142:145], v[208:211], v[74:77]
	v_mfma_f32_16x16x32_bf16 v[90:93], v[142:145], v[200:203], v[90:93]
	v_mfma_f32_16x16x32_bf16 v[90:93], v[138:141], v[190:193], v[90:93]
	v_mfma_f32_16x16x32_bf16 v[106:109], v[138:141], v[182:185], v[106:109]
	v_mfma_f32_16x16x32_bf16 v[106:109], v[142:145], v[186:189], v[106:109]
	v_mfma_f32_16x16x32_bf16 v[130:133], v[142:145], v[178:181], v[130:133]
	v_mfma_f32_16x16x32_bf16 v[130:133], v[138:141], v[174:177], v[130:133]
	s_setprio 0
	s_setprio 1
	v_mfma_f32_16x16x32_bf16 v[118:121], v[146:149], v[174:177], v[118:121]
	v_mfma_f32_16x16x32_bf16 v[118:121], v[150:153], v[178:181], v[118:121]
	v_mfma_f32_16x16x32_bf16 v[102:105], v[150:153], v[186:189], v[102:105]
	v_mfma_f32_16x16x32_bf16 v[102:105], v[146:149], v[182:185], v[102:105]
	v_mfma_f32_16x16x32_bf16 v[86:89], v[146:149], v[190:193], v[86:89]
	v_mfma_f32_16x16x32_bf16 v[86:89], v[150:153], v[200:203], v[86:89]
	v_mfma_f32_16x16x32_bf16 v[70:73], v[150:153], v[208:211], v[70:73]
	v_mfma_f32_16x16x32_bf16 v[70:73], v[146:149], v[204:207], v[70:73]
	v_mfma_f32_16x16x32_bf16 v[66:69], v[154:157], v[204:207], v[66:69]
	v_mfma_f32_16x16x32_bf16 v[66:69], v[158:161], v[208:211], v[66:69]
	v_mfma_f32_16x16x32_bf16 v[82:85], v[158:161], v[200:203], v[82:85]
	v_mfma_f32_16x16x32_bf16 v[82:85], v[154:157], v[190:193], v[82:85]
	v_mfma_f32_16x16x32_bf16 v[98:101], v[154:157], v[182:185], v[98:101]
	v_mfma_f32_16x16x32_bf16 v[98:101], v[158:161], v[186:189], v[98:101]
	v_mfma_f32_16x16x32_bf16 v[114:117], v[158:161], v[178:181], v[114:117]
	v_mfma_f32_16x16x32_bf16 v[114:117], v[154:157], v[174:177], v[114:117]
	s_setprio 0
	s_barrier
	s_add_i32 s12, s23, s42
	v_lshl_add_u64 v[212:213], v[212:213], 0, s[62:63]
	s_mov_b32 m0, s12
	ds_read_b128 v[174:177], v198 offset:49152
	ds_read_b128 v[178:181], v198 offset:50176
	ds_read_b128 v[182:185], v198 offset:51200
	ds_read_b128 v[186:189], v198 offset:52224
	ds_read_b128 v[190:193], v198 offset:53248
	ds_read_b128 v[200:203], v198 offset:54272
	ds_read_b128 v[204:207], v198 offset:55296
	ds_read_b128 v[208:211], v198 offset:56320
	global_load_lds_dwordx4 v[212:213], off
	s_add_i32 m0, s12, 0x2000
	s_add_u32 s12, s50, 0x158080
	v_lshl_add_u64 v[212:213], v[232:233], 0, s[62:63]
	s_addc_u32 s13, s51, 0
	s_add_i32 s23, s24, s42
	global_load_lds_dwordx4 v[212:213], off
	v_lshl_add_u64 v[212:213], s[12:13], 0, v[164:165]
	s_mov_b32 m0, s23
	s_nop 0
	global_load_lds_dwordx4 v[212:213], off
	v_lshl_add_u64 v[212:213], s[12:13], 0, v[168:169]
	s_add_i32 m0, s23, 0x2000
	s_nop 0
	global_load_lds_dwordx4 v[212:213], off
	v_lshl_add_u64 v[212:213], v[234:235], 0, s[62:63]
	s_mov_b32 m0, s1
	s_nop 0
	global_load_lds_dwordx4 v[212:213], off
	v_lshl_add_u64 v[212:213], v[236:237], 0, s[62:63]
	s_mov_b32 m0, s52
	s_nop 0
	global_load_lds_dwordx4 v[212:213], off
	s_waitcnt vmcnt(8)
	s_waitcnt lgkmcnt(0)
	v_mfma_f32_16x16x32_bf16 v[62:65], v[122:125], v[174:177], v[62:65]
	v_mfma_f32_16x16x32_bf16 v[62:65], v[126:129], v[178:181], v[62:65]
	v_mfma_f32_16x16x32_bf16 v[46:49], v[126:129], v[186:189], v[46:49]
	v_mfma_f32_16x16x32_bf16 v[46:49], v[122:125], v[182:185], v[46:49]
	s_barrier
	s_setprio 1
	s_waitcnt lgkmcnt(0)
	v_mfma_f32_16x16x32_bf16 v[30:33], v[122:125], v[190:193], v[30:33]
	v_mfma_f32_16x16x32_bf16 v[30:33], v[126:129], v[200:203], v[30:33]
	v_mfma_f32_16x16x32_bf16 v[14:17], v[126:129], v[208:211], v[14:17]
	v_mfma_f32_16x16x32_bf16 v[14:17], v[122:125], v[204:207], v[14:17]
	v_mfma_f32_16x16x32_bf16 v[10:13], v[138:141], v[204:207], v[10:13]
	v_mfma_f32_16x16x32_bf16 v[10:13], v[142:145], v[208:211], v[10:13]
	v_mfma_f32_16x16x32_bf16 v[26:29], v[142:145], v[200:203], v[26:29]
	v_mfma_f32_16x16x32_bf16 v[26:29], v[138:141], v[190:193], v[26:29]
	v_mfma_f32_16x16x32_bf16 v[42:45], v[138:141], v[182:185], v[42:45]
	v_mfma_f32_16x16x32_bf16 v[42:45], v[142:145], v[186:189], v[42:45]
	v_mfma_f32_16x16x32_bf16 v[58:61], v[142:145], v[178:181], v[58:61]
	v_mfma_f32_16x16x32_bf16 v[58:61], v[138:141], v[174:177], v[58:61]
	s_setprio 0
	s_setprio 1
	v_mfma_f32_16x16x32_bf16 v[54:57], v[146:149], v[174:177], v[54:57]
	v_mfma_f32_16x16x32_bf16 v[54:57], v[150:153], v[178:181], v[54:57]
	v_mfma_f32_16x16x32_bf16 v[38:41], v[150:153], v[186:189], v[38:41]
	v_mfma_f32_16x16x32_bf16 v[38:41], v[146:149], v[182:185], v[38:41]
	v_mfma_f32_16x16x32_bf16 v[22:25], v[146:149], v[190:193], v[22:25]
	v_mfma_f32_16x16x32_bf16 v[22:25], v[150:153], v[200:203], v[22:25]
	v_mfma_f32_16x16x32_bf16 v[6:9], v[150:153], v[208:211], v[6:9]
	v_mfma_f32_16x16x32_bf16 v[6:9], v[146:149], v[204:207], v[6:9]
	v_mfma_f32_16x16x32_bf16 v[2:5], v[154:157], v[204:207], v[2:5]
	v_mfma_f32_16x16x32_bf16 v[2:5], v[158:161], v[208:211], v[2:5]
	v_mfma_f32_16x16x32_bf16 v[18:21], v[158:161], v[200:203], v[18:21]
	v_mfma_f32_16x16x32_bf16 v[18:21], v[154:157], v[190:193], v[18:21]
	v_mfma_f32_16x16x32_bf16 v[34:37], v[154:157], v[182:185], v[34:37]
	v_mfma_f32_16x16x32_bf16 v[34:37], v[158:161], v[186:189], v[34:37]
	v_mfma_f32_16x16x32_bf16 v[50:53], v[158:161], v[178:181], v[50:53]
	v_mfma_f32_16x16x32_bf16 v[50:53], v[154:157], v[174:177], v[50:53]
	s_setprio 0
	s_barrier
	s_add_i32 s22, s22, 2
	s_add_u32 s20, s20, 0x100
	s_addc_u32 s21, s21, 0
	s_cmpk_gt_u32 s22, 0x53
	s_mov_b64 s[12:13], s[10:11]
	s_cbranch_scc0 .LBB0_238
	s_and_b64 vcc, exec, s[2:3]
	s_cbranch_vccz .LBB0_241
	s_barrier

.LBB0_340:
	s_add_u32 s22, s46, 0xfff80080
	s_addc_u32 s23, s47, -1
	s_add_i32 s24, 0, 0x10000
	s_cmp_eq_u32 s21, 28
	s_cselect_b32 s51, s1, s23
	s_cselect_b32 s50, s13, s22
	v_add_u32_e32 v148, s24, v152
	s_cselect_b32 s49, s11, s20
	s_cselect_b32 s48, s18, s19
	s_add_i32 s25, 0, 0x14000
	ds_read_b128 v[144:147], v148
	ds_read_b128 v[156:159], v148 offset:1024
	ds_read_b128 v[160:163], v148 offset:2048
	ds_read_b128 v[164:167], v148 offset:3072
	v_add_u32_e32 v148, s25, v152
	ds_read_b128 v[168:171], v148
	ds_read_b128 v[172:175], v148 offset:1024
	ds_read_b128 v[176:179], v148 offset:2048
	ds_read_b128 v[180:183], v148 offset:3072
	v_lshl_add_u64 v[148:149], s[46:47], 0, v[140:141]
	s_add_i32 m0, s3, 0xc000
	ds_read_b128 v[184:187], v154
	ds_read_b128 v[188:191], v154 offset:1024
	ds_read_b128 v[192:195], v154 offset:2048
	ds_read_b128 v[196:199], v154 offset:3072
	ds_read_b128 v[200:203], v154 offset:4096
	ds_read_b128 v[204:207], v154 offset:5120
	ds_read_b128 v[208:211], v154 offset:6144
	ds_read_b128 v[232:235], v154 offset:7168
	global_load_lds_dwordx4 v[148:149], off
	v_lshl_add_u64 v[148:149], s[46:47], 0, v[142:143]
	s_add_i32 m0, s3, 0xe000
	s_nop 0
	global_load_lds_dwordx4 v[148:149], off
	s_waitcnt vmcnt(8)
	s_waitcnt lgkmcnt(0)
	v_mfma_f32_16x16x32_bf16 v[126:129], v[144:147], v[184:187], v[126:129]
	v_mfma_f32_16x16x32_bf16 v[126:129], v[156:159], v[188:191], v[126:129]
	v_mfma_f32_16x16x32_bf16 v[110:113], v[156:159], v[196:199], v[110:113]
	v_mfma_f32_16x16x32_bf16 v[110:113], v[144:147], v[192:195], v[110:113]
	s_barrier
	s_setprio 1
	s_waitcnt lgkmcnt(0)
	v_mfma_f32_16x16x32_bf16 v[94:97], v[144:147], v[200:203], v[94:97]
	v_mfma_f32_16x16x32_bf16 v[94:97], v[156:159], v[204:207], v[94:97]
	v_mfma_f32_16x16x32_bf16 v[78:81], v[156:159], v[232:235], v[78:81]
	v_mfma_f32_16x16x32_bf16 v[78:81], v[144:147], v[208:211], v[78:81]
	v_mfma_f32_16x16x32_bf16 v[74:77], v[160:163], v[208:211], v[74:77]
	v_mfma_f32_16x16x32_bf16 v[74:77], v[164:167], v[232:235], v[74:77]
	v_mfma_f32_16x16x32_bf16 v[90:93], v[164:167], v[204:207], v[90:93]
	v_mfma_f32_16x16x32_bf16 v[90:93], v[160:163], v[200:203], v[90:93]
	v_mfma_f32_16x16x32_bf16 v[106:109], v[160:163], v[192:195], v[106:109]
	v_mfma_f32_16x16x32_bf16 v[106:109], v[164:167], v[196:199], v[106:109]
	v_mfma_f32_16x16x32_bf16 v[122:125], v[164:167], v[188:191], v[122:125]
	v_mfma_f32_16x16x32_bf16 v[122:125], v[160:163], v[184:187], v[122:125]
	s_setprio 0
	s_setprio 1
	v_mfma_f32_16x16x32_bf16 v[118:121], v[168:171], v[184:187], v[118:121]
	v_mfma_f32_16x16x32_bf16 v[118:121], v[172:175], v[188:191], v[118:121]
	v_mfma_f32_16x16x32_bf16 v[102:105], v[172:175], v[196:199], v[102:105]
	v_mfma_f32_16x16x32_bf16 v[102:105], v[168:171], v[192:195], v[102:105]
	v_mfma_f32_16x16x32_bf16 v[86:89], v[168:171], v[200:203], v[86:89]
	v_mfma_f32_16x16x32_bf16 v[86:89], v[172:175], v[204:207], v[86:89]
	v_mfma_f32_16x16x32_bf16 v[70:73], v[172:175], v[232:235], v[70:73]
	v_mfma_f32_16x16x32_bf16 v[70:73], v[168:171], v[208:211], v[70:73]
	v_mfma_f32_16x16x32_bf16 v[66:69], v[176:179], v[208:211], v[66:69]
	v_mfma_f32_16x16x32_bf16 v[66:69], v[180:183], v[232:235], v[66:69]
	v_mfma_f32_16x16x32_bf16 v[82:85], v[180:183], v[204:207], v[82:85]
	v_mfma_f32_16x16x32_bf16 v[82:85], v[176:179], v[200:203], v[82:85]
	v_mfma_f32_16x16x32_bf16 v[98:101], v[176:179], v[192:195], v[98:101]
	v_mfma_f32_16x16x32_bf16 v[98:101], v[180:183], v[196:199], v[98:101]
	v_mfma_f32_16x16x32_bf16 v[114:117], v[180:183], v[188:191], v[114:117]
	v_mfma_f32_16x16x32_bf16 v[114:117], v[176:179], v[184:187], v[114:117]
	s_setprio 0
	s_barrier
	s_add_i32 s22, s24, s16
	v_lshl_add_u64 v[148:149], s[48:49], 0, v[134:135]
	s_mov_b32 m0, s22
	ds_read_b128 v[184:187], v154 offset:16384
	ds_read_b128 v[188:191], v154 offset:17408
	ds_read_b128 v[192:195], v154 offset:18432
	ds_read_b128 v[196:199], v154 offset:19456
	ds_read_b128 v[200:203], v154 offset:20480
	ds_read_b128 v[204:207], v154 offset:21504
	ds_read_b128 v[208:211], v154 offset:22528
	ds_read_b128 v[232:235], v154 offset:23552
	global_load_lds_dwordx4 v[148:149], off
	s_add_i32 m0, s22, 0x2000
	s_add_u32 s22, s48, 0x80000
	v_lshl_add_u64 v[212:213], s[48:49], 0, v[130:131]
	s_addc_u32 s23, s49, 0
	s_add_i32 s24, s25, s16
	global_load_lds_dwordx4 v[212:213], off
	v_lshl_add_u64 v[236:237], s[22:23], 0, v[134:135]
	s_mov_b32 m0, s24
	v_lshl_add_u64 v[238:239], s[50:51], 0, v[132:133]
	global_load_lds_dwordx4 v[236:237], off
	v_lshl_add_u64 v[236:237], s[22:23], 0, v[130:131]
	s_add_i32 m0, s24, 0x2000
	s_nop 0
	global_load_lds_dwordx4 v[236:237], off
	v_lshl_add_u64 v[236:237], s[50:51], 0, v[136:137]
	s_mov_b32 m0, s3
	s_nop 0
	global_load_lds_dwordx4 v[236:237], off
	s_mov_b32 m0, s55
	s_nop 0
	global_load_lds_dwordx4 v[238:239], off
	s_waitcnt vmcnt(8)
	s_waitcnt lgkmcnt(0)
	v_mfma_f32_16x16x32_bf16 v[62:65], v[144:147], v[184:187], v[62:65]
	v_mfma_f32_16x16x32_bf16 v[62:65], v[156:159], v[188:191], v[62:65]
	v_mfma_f32_16x16x32_bf16 v[46:49], v[156:159], v[196:199], v[46:49]
	v_mfma_f32_16x16x32_bf16 v[46:49], v[144:147], v[192:195], v[46:49]
	s_barrier
	s_setprio 1
	s_waitcnt lgkmcnt(0)
	v_mfma_f32_16x16x32_bf16 v[30:33], v[144:147], v[200:203], v[30:33]
	v_mfma_f32_16x16x32_bf16 v[30:33], v[156:159], v[204:207], v[30:33]
	v_mfma_f32_16x16x32_bf16 v[14:17], v[156:159], v[232:235], v[14:17]
	v_mfma_f32_16x16x32_bf16 v[14:17], v[144:147], v[208:211], v[14:17]
	v_mfma_f32_16x16x32_bf16 v[10:13], v[160:163], v[208:211], v[10:13]
	v_mfma_f32_16x16x32_bf16 v[10:13], v[164:167], v[232:235], v[10:13]
	v_mfma_f32_16x16x32_bf16 v[26:29], v[164:167], v[204:207], v[26:29]
	v_mfma_f32_16x16x32_bf16 v[26:29], v[160:163], v[200:203], v[26:29]
	v_mfma_f32_16x16x32_bf16 v[42:45], v[160:163], v[192:195], v[42:45]
	v_mfma_f32_16x16x32_bf16 v[42:45], v[164:167], v[196:199], v[42:45]
	v_mfma_f32_16x16x32_bf16 v[58:61], v[164:167], v[188:191], v[58:61]
	v_mfma_f32_16x16x32_bf16 v[58:61], v[160:163], v[184:187], v[58:61]
	s_setprio 0
	s_setprio 1
	v_mfma_f32_16x16x32_bf16 v[54:57], v[168:171], v[184:187], v[54:57]
	v_mfma_f32_16x16x32_bf16 v[54:57], v[172:175], v[188:191], v[54:57]
	v_mfma_f32_16x16x32_bf16 v[38:41], v[172:175], v[196:199], v[38:41]
	v_mfma_f32_16x16x32_bf16 v[38:41], v[168:171], v[192:195], v[38:41]
	v_mfma_f32_16x16x32_bf16 v[22:25], v[168:171], v[200:203], v[22:25]
	v_mfma_f32_16x16x32_bf16 v[22:25], v[172:175], v[204:207], v[22:25]
	v_mfma_f32_16x16x32_bf16 v[6:9], v[172:175], v[232:235], v[6:9]
	v_mfma_f32_16x16x32_bf16 v[6:9], v[168:171], v[208:211], v[6:9]
	v_mfma_f32_16x16x32_bf16 v[2:5], v[176:179], v[208:211], v[2:5]
	v_mfma_f32_16x16x32_bf16 v[2:5], v[180:183], v[232:235], v[2:5]
	v_mfma_f32_16x16x32_bf16 v[18:21], v[180:183], v[204:207], v[18:21]
	v_mfma_f32_16x16x32_bf16 v[18:21], v[176:179], v[200:203], v[18:21]
	v_mfma_f32_16x16x32_bf16 v[34:37], v[176:179], v[192:195], v[34:37]
	v_mfma_f32_16x16x32_bf16 v[34:37], v[180:183], v[196:199], v[34:37]
	v_mfma_f32_16x16x32_bf16 v[50:53], v[180:183], v[188:191], v[50:53]
	v_mfma_f32_16x16x32_bf16 v[50:53], v[176:179], v[184:187], v[50:53]
	s_setprio 0
	s_barrier
	s_add_i32 s24, 0, 0x18000
	v_add_u32_e32 v155, s24, v152
	s_add_i32 s25, 0, 0x1c000
	ds_read_b128 v[144:147], v155
	ds_read_b128 v[156:159], v155 offset:1024
	ds_read_b128 v[160:163], v155 offset:2048
	ds_read_b128 v[164:167], v155 offset:3072
	v_add_u32_e32 v155, s25, v152
	ds_read_b128 v[168:171], v155
	ds_read_b128 v[172:175], v155 offset:1024
	ds_read_b128 v[176:179], v155 offset:2048
	ds_read_b128 v[180:183], v155 offset:3072
	s_add_u32 s22, s50, 0x80000
	s_addc_u32 s23, s51, 0
	s_mov_b32 m0, s57
	v_lshl_add_u64 v[240:241], s[22:23], 0, v[136:137]
	ds_read_b128 v[184:187], v154 offset:32768
	ds_read_b128 v[188:191], v154 offset:33792
	ds_read_b128 v[192:195], v154 offset:34816
	ds_read_b128 v[196:199], v154 offset:35840
	ds_read_b128 v[200:203], v154 offset:36864
	ds_read_b128 v[204:207], v154 offset:37888
	ds_read_b128 v[208:211], v154 offset:38912
	ds_read_b128 v[232:235], v154 offset:39936
	global_load_lds_dwordx4 v[240:241], off
	v_lshl_add_u64 v[240:241], s[22:23], 0, v[132:133]
	s_mov_b32 m0, s68
	s_nop 0
	global_load_lds_dwordx4 v[240:241], off
	s_waitcnt vmcnt(8)
	s_waitcnt lgkmcnt(0)
	v_mfma_f32_16x16x32_bf16 v[126:129], v[144:147], v[184:187], v[126:129]
	v_mfma_f32_16x16x32_bf16 v[126:129], v[156:159], v[188:191], v[126:129]
	v_mfma_f32_16x16x32_bf16 v[110:113], v[156:159], v[196:199], v[110:113]
	v_mfma_f32_16x16x32_bf16 v[110:113], v[144:147], v[192:195], v[110:113]
	s_barrier
	s_setprio 1
	s_waitcnt lgkmcnt(0)
	v_mfma_f32_16x16x32_bf16 v[94:97], v[144:147], v[200:203], v[94:97]
	v_mfma_f32_16x16x32_bf16 v[94:97], v[156:159], v[204:207], v[94:97]
	v_mfma_f32_16x16x32_bf16 v[78:81], v[156:159], v[232:235], v[78:81]
	v_mfma_f32_16x16x32_bf16 v[78:81], v[144:147], v[208:211], v[78:81]
	v_mfma_f32_16x16x32_bf16 v[74:77], v[160:163], v[208:211], v[74:77]
	v_mfma_f32_16x16x32_bf16 v[74:77], v[164:167], v[232:235], v[74:77]
	v_mfma_f32_16x16x32_bf16 v[90:93], v[164:167], v[204:207], v[90:93]
	v_mfma_f32_16x16x32_bf16 v[90:93], v[160:163], v[200:203], v[90:93]
	v_mfma_f32_16x16x32_bf16 v[106:109], v[160:163], v[192:195], v[106:109]
	v_mfma_f32_16x16x32_bf16 v[106:109], v[164:167], v[196:199], v[106:109]
	v_mfma_f32_16x16x32_bf16 v[122:125], v[164:167], v[188:191], v[122:125]
	v_mfma_f32_16x16x32_bf16 v[122:125], v[160:163], v[184:187], v[122:125]
	s_setprio 0
	s_setprio 1
	v_mfma_f32_16x16x32_bf16 v[118:121], v[168:171], v[184:187], v[118:121]
	v_mfma_f32_16x16x32_bf16 v[118:121], v[172:175], v[188:191], v[118:121]
	v_mfma_f32_16x16x32_bf16 v[102:105], v[172:175], v[196:199], v[102:105]
	v_mfma_f32_16x16x32_bf16 v[102:105], v[168:171], v[192:195], v[102:105]
	v_mfma_f32_16x16x32_bf16 v[86:89], v[168:171], v[200:203], v[86:89]
	v_mfma_f32_16x16x32_bf16 v[86:89], v[172:175], v[204:207], v[86:89]
	v_mfma_f32_16x16x32_bf16 v[70:73], v[172:175], v[232:235], v[70:73]
	v_mfma_f32_16x16x32_bf16 v[70:73], v[168:171], v[208:211], v[70:73]
	v_mfma_f32_16x16x32_bf16 v[66:69], v[176:179], v[208:211], v[66:69]
	v_mfma_f32_16x16x32_bf16 v[66:69], v[180:183], v[232:235], v[66:69]
	v_mfma_f32_16x16x32_bf16 v[82:85], v[180:183], v[204:207], v[82:85]
	v_mfma_f32_16x16x32_bf16 v[82:85], v[176:179], v[200:203], v[82:85]
	v_mfma_f32_16x16x32_bf16 v[98:101], v[176:179], v[192:195], v[98:101]
	v_mfma_f32_16x16x32_bf16 v[98:101], v[180:183], v[196:199], v[98:101]
	v_mfma_f32_16x16x32_bf16 v[114:117], v[180:183], v[188:191], v[114:117]
	v_mfma_f32_16x16x32_bf16 v[114:117], v[176:179], v[184:187], v[114:117]
	s_setprio 0
	s_barrier
	s_add_i32 s22, s24, s16
	v_lshl_add_u64 v[148:149], v[148:149], 0, s[62:63]
	s_mov_b32 m0, s22
	ds_read_b128 v[184:187], v154 offset:49152
	ds_read_b128 v[188:191], v154 offset:50176
	ds_read_b128 v[192:195], v154 offset:51200
	ds_read_b128 v[196:199], v154 offset:52224
	ds_read_b128 v[200:203], v154 offset:53248
	ds_read_b128 v[204:207], v154 offset:54272
	ds_read_b128 v[208:211], v154 offset:55296
	ds_read_b128 v[232:235], v154 offset:56320
	global_load_lds_dwordx4 v[148:149], off
	s_add_i32 m0, s22, 0x2000
	s_add_u32 s22, s48, 0x80080
	v_lshl_add_u64 v[148:149], v[212:213], 0, s[62:63]
	s_addc_u32 s23, s49, 0
	s_add_i32 s24, s25, s16
	global_load_lds_dwordx4 v[148:149], off
	v_lshl_add_u64 v[148:149], s[22:23], 0, v[134:135]
	s_mov_b32 m0, s24
	s_nop 0
	global_load_lds_dwordx4 v[148:149], off
	v_lshl_add_u64 v[148:149], s[22:23], 0, v[130:131]
	s_add_i32 m0, s24, 0x2000
	s_nop 0
	global_load_lds_dwordx4 v[148:149], off
	v_lshl_add_u64 v[148:149], v[236:237], 0, s[62:63]
	s_mov_b32 m0, s69
	s_nop 0
	global_load_lds_dwordx4 v[148:149], off
	v_lshl_add_u64 v[148:149], v[238:239], 0, s[62:63]
	s_mov_b32 m0, s70
	s_nop 0
	global_load_lds_dwordx4 v[148:149], off
	s_waitcnt vmcnt(8)
	s_waitcnt lgkmcnt(0)
	v_mfma_f32_16x16x32_bf16 v[62:65], v[144:147], v[184:187], v[62:65]
	v_mfma_f32_16x16x32_bf16 v[62:65], v[156:159], v[188:191], v[62:65]
	v_mfma_f32_16x16x32_bf16 v[46:49], v[156:159], v[196:199], v[46:49]
	v_mfma_f32_16x16x32_bf16 v[46:49], v[144:147], v[192:195], v[46:49]
	s_barrier
	s_setprio 1
	s_waitcnt lgkmcnt(0)
	v_mfma_f32_16x16x32_bf16 v[30:33], v[144:147], v[200:203], v[30:33]
	v_mfma_f32_16x16x32_bf16 v[30:33], v[156:159], v[204:207], v[30:33]
	v_mfma_f32_16x16x32_bf16 v[14:17], v[156:159], v[232:235], v[14:17]
	v_mfma_f32_16x16x32_bf16 v[14:17], v[144:147], v[208:211], v[14:17]
	v_mfma_f32_16x16x32_bf16 v[10:13], v[160:163], v[208:211], v[10:13]
	v_mfma_f32_16x16x32_bf16 v[10:13], v[164:167], v[232:235], v[10:13]
	v_mfma_f32_16x16x32_bf16 v[26:29], v[164:167], v[204:207], v[26:29]
	v_mfma_f32_16x16x32_bf16 v[26:29], v[160:163], v[200:203], v[26:29]
	v_mfma_f32_16x16x32_bf16 v[42:45], v[160:163], v[192:195], v[42:45]
	v_mfma_f32_16x16x32_bf16 v[42:45], v[164:167], v[196:199], v[42:45]
	v_mfma_f32_16x16x32_bf16 v[58:61], v[164:167], v[188:191], v[58:61]
	v_mfma_f32_16x16x32_bf16 v[58:61], v[160:163], v[184:187], v[58:61]
	s_setprio 0
	s_setprio 1
	v_mfma_f32_16x16x32_bf16 v[54:57], v[168:171], v[184:187], v[54:57]
	v_mfma_f32_16x16x32_bf16 v[54:57], v[172:175], v[188:191], v[54:57]
	v_mfma_f32_16x16x32_bf16 v[38:41], v[172:175], v[196:199], v[38:41]
	v_mfma_f32_16x16x32_bf16 v[38:41], v[168:171], v[192:195], v[38:41]
	v_mfma_f32_16x16x32_bf16 v[22:25], v[168:171], v[200:203], v[22:25]
	v_mfma_f32_16x16x32_bf16 v[22:25], v[172:175], v[204:207], v[22:25]
	v_mfma_f32_16x16x32_bf16 v[6:9], v[172:175], v[232:235], v[6:9]
	v_mfma_f32_16x16x32_bf16 v[6:9], v[168:171], v[208:211], v[6:9]
	v_mfma_f32_16x16x32_bf16 v[2:5], v[176:179], v[208:211], v[2:5]
	v_mfma_f32_16x16x32_bf16 v[2:5], v[180:183], v[232:235], v[2:5]
	v_mfma_f32_16x16x32_bf16 v[18:21], v[180:183], v[204:207], v[18:21]
	v_mfma_f32_16x16x32_bf16 v[18:21], v[176:179], v[200:203], v[18:21]
	v_mfma_f32_16x16x32_bf16 v[34:37], v[176:179], v[192:195], v[34:37]
	v_mfma_f32_16x16x32_bf16 v[34:37], v[180:183], v[196:199], v[34:37]
	v_mfma_f32_16x16x32_bf16 v[50:53], v[180:183], v[188:191], v[50:53]
	v_mfma_f32_16x16x32_bf16 v[50:53], v[176:179], v[184:187], v[50:53]
	s_setprio 0
	s_barrier
	s_add_i32 s21, s21, 2
	s_add_u32 s46, s46, 0x100
	s_addc_u32 s47, s47, 0
	s_add_u32 s19, s19, 0x100
	s_addc_u32 s20, s20, 0
	s_cmp_gt_u32 s21, 29
	s_cbranch_scc0 .LBB0_340
	s_and_b64 vcc, exec, s[8:9]
	s_cbranch_vccz .LBB0_343
	s_barrier
